# v13 plus unconditional next-tile K/V loads in the MLA loop (in-bounds dummy rows on the last iteration): skip branch, conservative vmcnt(2)/(1)/(0) ladder and loop-top vmcnt(0) deleted
# speedup vs baseline: 1.0045x; 1.0045x over previous
; #define SBAR() __builtin_amdgcn_sched_barrier(0)
; #define SLOAD(i, k0) do { st_[i].vs = *reinterpret_cast<const bf16x8*>(&Vh[(size_t)((k0) + sr) * LDK + sc]); \
;     st_[i].ks = *reinterpret_cast<const bf16x8*>(&Kh[(size_t)((k0) + sr) * LDK + sc]); \
;     if (DQ == 96) st_[i].kr = *reinterpret_cast<const bf16x8*>(&Kr[(size_t)((k0) + sr2) * 32 + sc2]); } while (0)
; #define SWRITE(b, i) do { *(bf16x8*)(V_lds + (b) * SHM_V + vst0) = st_[i].vs; *(bf16x8*)(K_lds + (b) * SHM_K + kst0) = st_[i].ks; \
;     if (DQ == 96) { if (tid < 256) *(bf16x8*)(K_lds + (b) * SHM_K + kst2) = st_[i].kr; } } while (0)
; #define SWAIT() do { if (DQ == 96) asm volatile("s_waitcnt vmcnt(3)" ::: "memory"); else asm volatile("s_waitcnt vmcnt(2)" ::: "memory"); } while (0)
; #define SLOAD(i, k0) do { st_[i].vs = *reinterpret_cast<const bf16x8*>(&Vh[(size_t)((k0) + sr) * LDK + sc]); \
;     st_[i].ks = *reinterpret_cast<const bf16x8*>(&Kh[(size_t)((k0) + sr) * LDK + sc]); \
;     if (DQ == 96) st_[i].kr = *reinterpret_cast<const bf16x8*>(&Kr[(size_t)((k0) + sr2) * 32 + sc2]); } while (0)
; #define SWRITE(b, i) do { *(bf16x8*)(V_lds + (b) * SHM_V + vst0) = st_[i].vs; *(bf16x8*)(K_lds + (b) * SHM_K + kst0) = st_[i].ks; \
;     if (DQ == 96) { if (tid < 256) *(bf16x8*)(K_lds + (b) * SHM_K + kst2) = st_[i].kr; } } while (0)
; #define SWAIT() do { if (DQ == 96) asm volatile("s_waitcnt vmcnt(3)" ::: "memory"); else asm volatile("s_waitcnt vmcnt(2)" ::: "memory"); } while (0)
; template <int DQ, bool WIN, int LDQ, int LDK> ...
;     ...
;     for (int j = 1; j + 1 < NT; j += 2) {
;         SBAR(); qkt<DQ>(pB0, pB1, K_lds + SHM_K, qr, minit, r32, hi);
;         finish(pA0, pA1); SBAR();
;         SLOAD(SO, KBASE(j + 2)); SBAR();
;         pv(vb0);
;         __syncthreads(); SWAIT(); SWRITE(0, SE);
;         lsum_upd();
;         if (WIN) win_mask(pB0, pB1, qrow - KBASE(j), hi);
;         exp16(pB0);
;         __syncthreads();
;         SBAR(); qkt<DQ>(pA0, pA1, K_lds, qr, minit, r32, hi);
.LBB0_1093:
	s_or_b64 exec, exec, s[18:19]
	v_xor_b32_e32 v192, 0xc000, v192
	v_xor_b32_e32 v194, 0xc000, v194
	v_xor_b32_e32 v190, 0xc000, v190
	v_exp_f32_e32 v161, v96
	v_exp_f32_e32 v196, v97
	v_mfma_f32_16x16x32_bf16 v[32:35], v[80:83], v[36:39], v[32:35]
	v_exp_f32_e32 v158, v98
	v_exp_f32_e32 v168, v99
	v_exp_f32_e32 v159, v100
	v_exp_f32_e32 v169, v101
	v_exp_f32_e32 v160, v102
	v_exp_f32_e32 v195, v103
	v_exp_f32_e32 v154, v105
	v_mfma_f32_16x16x32_bf16 v[32:35], v[84:87], v[36:39], v[32:35]
	v_exp_f32_e32 v155, v107
	v_exp_f32_e32 v156, v109
	v_exp_f32_e32 v157, v111
	s_mov_b64 s[34:35], 0x2000
	s_mov_b64 s[18:19], 0x80000
	v_lshl_add_u64 v[162:163], v[162:163], 0, s[34:35]
	v_lshl_add_u64 v[164:165], v[164:165], 0, s[18:19]
	v_mfma_f32_16x16x32_bf16 v[32:35], v[88:91], v[36:39], v[32:35]
	v_lshl_add_u64 v[166:167], v[166:167], 0, s[34:35]
	s_and_b64 vcc, exec, s[4:5]
	s_waitcnt lgkmcnt(0)
	s_barrier
	v_mfma_f32_16x16x32_bf16 v[32:35], v[92:95], v[36:39], v[32:35]
	v_exp_f32_e32 v150, v104
	v_exp_f32_e32 v151, v106
	v_exp_f32_e32 v152, v108
	v_exp_f32_e32 v153, v110
	s_cbranch_vccnz .LBB0_1100

; #define SBAR() __builtin_amdgcn_sched_barrier(0)
; #define SLOAD(i, k0) do { st_[i].vs = *reinterpret_cast<const bf16x8*>(&Vh[(size_t)((k0) + sr) * LDK + sc]); \
;     st_[i].ks = *reinterpret_cast<const bf16x8*>(&Kh[(size_t)((k0) + sr) * LDK + sc]); \
;     if (DQ == 96) st_[i].kr = *reinterpret_cast<const bf16x8*>(&Kr[(size_t)((k0) + sr2) * 32 + sc2]); } while (0)
; #define SWRITE(b, i) do { *(bf16x8*)(V_lds + (b) * SHM_V + vst0) = st_[i].vs; *(bf16x8*)(K_lds + (b) * SHM_K + kst0) = st_[i].ks; \
;     if (DQ == 96) { if (tid < 256) *(bf16x8*)(K_lds + (b) * SHM_K + kst2) = st_[i].kr; } } while (0)
; #define SWAIT() do { if (DQ == 96) asm volatile("s_waitcnt vmcnt(3)" ::: "memory"); else asm volatile("s_waitcnt vmcnt(2)" ::: "memory"); } while (0)
; #define SLOAD(i, k0) do { st_[i].vs = *reinterpret_cast<const bf16x8*>(&Vh[(size_t)((k0) + sr) * LDK + sc]); \
;     st_[i].ks = *reinterpret_cast<const bf16x8*>(&Kh[(size_t)((k0) + sr) * LDK + sc]); \
;     if (DQ == 96) st_[i].kr = *reinterpret_cast<const bf16x8*>(&Kr[(size_t)((k0) + sr2) * 32 + sc2]); } while (0)
; #define SWRITE(b, i) do { *(bf16x8*)(V_lds + (b) * SHM_V + vst0) = st_[i].vs; *(bf16x8*)(K_lds + (b) * SHM_K + kst0) = st_[i].ks; \
;     if (DQ == 96) { if (tid < 256) *(bf16x8*)(K_lds + (b) * SHM_K + kst2) = st_[i].kr; } } while (0)
; #define SWAIT() do { if (DQ == 96) asm volatile("s_waitcnt vmcnt(3)" ::: "memory"); else asm volatile("s_waitcnt vmcnt(2)" ::: "memory"); } while (0)
; template <int DQ, bool WIN, int LDQ, int LDK> ...
;     ...
;         lsum_upd();
;         if (WIN) win_mask(pB0, pB1, qrow - KBASE(j), hi);
;         exp16(pB0);
;         __syncthreads();
;         SBAR(); qkt<DQ>(pA0, pA1, K_lds, qr, minit, r32, hi);
;         finish(pB0, pB1); SBAR();
;         if (j + 3 < NT) SLOAD(SE, KBASE(j + 3)); SBAR();
;         pv(vb0 + SHM_V);
;         __syncthreads(); SWAIT(); SWRITE(1, SO);
;         lsum_upd();
;         if (WIN) win_mask(pA0, pA1, qrow - KBASE(j + 1), hi);
;         exp16(pA0);
;         __syncthreads();
;     }
.LBB0_1096:
	s_or_b64 exec, exec, s[4:5]
	s_add_i32 s17, s17, 2
	v_exp_f32_e32 v195, v96
	v_mfma_f32_16x16x32_bf16 v[32:35], v[68:71], v[36:39], v[32:35]
	v_exp_f32_e32 v204, v97
	v_exp_f32_e32 v205, v98
	v_exp_f32_e32 v206, v99
	v_exp_f32_e32 v207, v100
	v_exp_f32_e32 v208, v101
	v_exp_f32_e32 v209, v102
	v_exp_f32_e32 v210, v103
	v_mfma_f32_16x16x32_bf16 v[32:35], v[64:67], v[36:39], v[32:35]
	v_exp_f32_e32 v211, v104
	v_exp_f32_e32 v212, v105
	v_exp_f32_e32 v213, v106
	v_exp_f32_e32 v214, v107
	v_exp_f32_e32 v215, v108
	v_exp_f32_e32 v216, v109
	v_exp_f32_e32 v217, v110
	v_mfma_f32_16x16x32_bf16 v[32:35], v[76:79], v[36:39], v[32:35]
	v_exp_f32_e32 v218, v111
	s_waitcnt lgkmcnt(0)
	s_barrier
	v_mfma_f32_16x16x32_bf16 v[32:35], v[72:75], v[36:39], v[32:35]
	ds_read_b64_tr_b16 v[40:41], v190 offset:0
	ds_read_b64_tr_b16 v[42:43], v190 offset:0x400
	ds_read_b64_tr_b16 v[44:45], v190 offset:0x800
	ds_read_b64_tr_b16 v[46:47], v190 offset:0xc00
	ds_read_b128 v[196:199], v191 offset:23040
	ds_read_b128 v[64:67], v191 offset:16384
	ds_read_b128 v[200:203], v191 offset:16416
	v_exp_f32_e32 v95, v95
	v_exp_f32_e32 v219, v88
	v_exp_f32_e32 v220, v89
	s_waitcnt lgkmcnt(1)
	v_mfma_f32_32x32x16_bf16 v[96:111], v[64:67], v[134:137], v[48:63]
	v_exp_f32_e32 v221, v90
	v_exp_f32_e32 v222, v91
	v_exp_f32_e32 v223, v92
	v_exp_f32_e32 v224, v93
	v_exp_f32_e32 v225, v94
	v_mfma_f32_32x32x16_bf16 v[64:79], v[196:199], v[134:137], v[48:63]
	ds_read_b128 v[196:199], v191 offset:23072
	s_waitcnt lgkmcnt(1)
	v_mfma_f32_32x32x16_bf16 v[96:111], v[200:203], v[130:133], v[96:111]
	s_waitcnt lgkmcnt(0)
	v_mfma_f32_32x32x16_bf16 v[64:79], v[196:199], v[130:133], v[64:79]
	ds_read_b128 v[196:199], v191 offset:16448
	ds_read_b128 v[200:203], v191 offset:23104
	s_waitcnt lgkmcnt(1)
	v_mfma_f32_32x32x16_bf16 v[96:111], v[196:199], v[126:129], v[96:111]
	s_waitcnt lgkmcnt(0)
	v_mfma_f32_32x32x16_bf16 v[64:79], v[200:203], v[126:129], v[64:79]
	ds_read_b128 v[196:199], v191 offset:16480
	ds_read_b128 v[200:203], v191 offset:23136
	s_waitcnt lgkmcnt(1)
	v_mfma_f32_32x32x16_bf16 v[96:111], v[196:199], v[122:125], v[96:111]
	s_waitcnt lgkmcnt(0)
	v_mfma_f32_32x32x16_bf16 v[64:79], v[200:203], v[122:125], v[64:79]
	ds_read_b128 v[196:199], v191 offset:16512
	ds_read_b128 v[200:203], v191 offset:23168
	s_waitcnt lgkmcnt(1)
	v_mfma_f32_32x32x16_bf16 v[96:111], v[196:199], v[118:121], v[96:111]
	s_waitcnt lgkmcnt(0)
	v_mfma_f32_32x32x16_bf16 v[64:79], v[200:203], v[118:121], v[64:79]
	ds_read_b128 v[196:199], v191 offset:16544
	ds_read_b128 v[200:203], v191 offset:23200
	s_waitcnt lgkmcnt(1)
	v_mfma_f32_32x32x16_bf16 v[96:111], v[196:199], v[114:117], v[96:111]
	v_exp_f32_e32 v196, v80
	v_exp_f32_e32 v197, v81
	v_exp_f32_e32 v198, v82
	v_exp_f32_e32 v199, v83
	v_cvt_pk_bf16_f32 v80, v195, v204
	v_cvt_pk_bf16_f32 v81, v205, v206
	v_cvt_pk_bf16_f32 v82, v207, v208
	s_waitcnt lgkmcnt(0)
	v_mfma_f32_32x32x16_bf16 v[64:79], v[200:203], v[114:117], v[64:79]
	v_exp_f32_e32 v200, v84
	v_exp_f32_e32 v201, v85
	v_exp_f32_e32 v202, v86
	v_exp_f32_e32 v203, v87
	v_cvt_pk_bf16_f32 v83, v209, v210
	v_cvt_pk_bf16_f32 v84, v211, v212
	v_cvt_pk_bf16_f32 v85, v213, v214
	v_cvt_pk_bf16_f32 v86, v215, v216
	v_cvt_pk_bf16_f32 v87, v217, v218
	v_cvt_pk_bf16_f32 v88, v196, v197
	v_cvt_pk_bf16_f32 v89, v198, v199
	v_cvt_pk_bf16_f32 v90, v200, v201
	v_cvt_pk_bf16_f32 v91, v202, v203
	v_cvt_pk_bf16_f32 v92, v219, v220
	v_cvt_pk_bf16_f32 v93, v221, v222
	v_cvt_pk_bf16_f32 v94, v223, v224
	v_cvt_pk_bf16_f32 v95, v225, v95
	s_cmpk_gt_u32 s17, 0x7c
	s_cselect_b64 s[4:5], -1, 0
	v_add_co_u32_e32 v142, vcc, 0x21900000, v168
	s_waitcnt vmcnt(3)
	v_lshl_add_u64 v[146:147], s[26:27], 0, v[162:163]
	v_addc_co_u32_e32 v143, vcc, 0, v169, vcc
	global_load_dwordx4 v[138:141], v[142:143], off offset:128
	s_nop 0
	global_load_dwordx4 v[142:145], v[142:143], off
	s_nop 0
	global_load_dwordx4 v[146:149], v[146:147], off
.LBB0_1098:
	ds_read_b64_tr_b16 v[204:205], v190 offset:0x1000
	ds_read_b64_tr_b16 v[206:207], v190 offset:0x1400
	ds_read_b64_tr_b16 v[208:209], v190 offset:0x1800
	ds_read_b64_tr_b16 v[210:211], v190 offset:0x1c00
	ds_read_b64_tr_b16 v[196:197], v190 offset:0x200
	ds_read_b64_tr_b16 v[198:199], v190 offset:0x600
	ds_read_b64_tr_b16 v[200:201], v190 offset:0xa00
	ds_read_b64_tr_b16 v[202:203], v190 offset:0xe00
	s_nop 0
	v_mfma_f32_32x32x16_bf16 v[0:15], v[80:83], v[40:43], v[0:15]
	v_mfma_f32_32x32x16_bf16 v[0:15], v[84:87], v[44:47], v[0:15]
	s_waitcnt lgkmcnt(6)
	v_mfma_f32_32x32x16_bf16 v[0:15], v[88:91], v[204:207], v[0:15]
	ds_read_b64_tr_b16 v[204:205], v190 offset:0x1200
	ds_read_b64_tr_b16 v[206:207], v190 offset:0x1600
	s_waitcnt lgkmcnt(6)
	v_mfma_f32_32x32x16_bf16 v[0:15], v[92:95], v[208:211], v[0:15]
	ds_read_b64_tr_b16 v[208:209], v190 offset:0x1a00
	ds_read_b64_tr_b16 v[210:211], v190 offset:0x1e00
	s_waitcnt lgkmcnt(0)
	v_mfma_f32_32x32x16_bf16 v[16:31], v[80:83], v[196:199], v[16:31]
	s_waitcnt vmcnt(3)
	ds_write_b128 v192, v[154:157] offset:8192
	ds_write_b128 v193, v[158:161] offset:29696
	v_mfma_f32_32x32x16_bf16 v[16:31], v[84:87], v[200:203], v[16:31]
	v_mfma_f32_32x32x16_bf16 v[16:31], v[88:91], v[204:207], v[16:31]
	v_mfma_f32_32x32x16_bf16 v[16:31], v[92:95], v[208:211], v[16:31]
	s_and_saveexec_b64 s[18:19], s[40:41]
	s_cbranch_execz .LBB0_1093
	ds_write_b128 v112, v[150:153] offset:29824
	s_branch .LBB0_1093
